# attention key loop: waves 4-7 lag by s_sleep 6 after each iteration barrier (phase offset between SIMD wave partners)
# baseline (speedup 1.0000x reference)
; #define GLDS(gp, lp) __builtin_amdgcn_global_load_lds((const unsigned*)(gp), (__attribute__((address_space(3))) unsigned*)(lp), 16, 0, 0)
; #define SB_ __builtin_amdgcn_sched_barrier(0)
; #define ATT64_STORE(base) do { \
;     { uint2* d = (uint2*)((base) + vlo0); d[0] = make_uint2(rv0.x, rv0.y); d[1] = make_uint2(rv0.z, rv0.w); } } while (0)
; DI void attn_item64(const Params& p, int it, char* smem) {
;     ...
;   const float negC = -(sqrtf(fmaxf(qsa, qsb)) * gk * 9.797959f * 1.01f);
;   f32x16 sinit;
; #pragma unroll
;   for (int i = 0; i < 16; ++i) sinit[i] = negC;
;   float la = 0.f, lb = 0.f;
;   const int kid0 = t, kid1 = (t & 255) + 512;
;   const bool k1v = t < 256;
;   const int kgo0 = (kid0 / 12) * QKD + (((kid0 % 12) ^ (((kid0 / 12) >> 2) & 3))) * 8, kgo1 = (kid1 / 12) * QKD + (((kid1 % 12) ^ (((kid1 / 12) >> 2) & 3))) * 8;
;   const int klo0 = kid0 * 16, klo1 = kid1 * 16;
;   const int vgo0 = (t >> 3) * NKEY + (t & 7) * 8;
;   const int vlo0 = KBYTES + (t >> 3) * VROW + (t & 7) * 16;
;   uint4 rv0;
;   GLDS(Kb + kgo0, smem + klo0); if (k1v) GLDS(Kb + kgo1, smem + klo1);
;   rv0 = *(const uint4*)(Vb + vgo0);
;   SB_;
;     ...
;   ATT64_STORE(smem);
;   __syncthreads();
.LBB0_547:
	s_or_b64 exec, exec, s[4:5]
	v_ashrrev_i32_e32 v11, 3, v7
	s_movk_i32 s6, 0x900
	v_mul_lo_u32 v12, v11, s6
	v_and_b32_e32 v18, 7, v7
	s_mul_i32 s4, s42, 0x48000
	v_lshl_or_b32 v12, v18, 3, v12
	s_mul_hi_u32 s5, s42, 0x48000
	s_add_u32 s4, s20, s4
	v_ashrrev_i32_e32 v13, 31, v12
	s_addc_u32 s5, s21, s5
	v_lshlrev_b64 v[16:17], 1, v[12:13]
	v_lshl_add_u64 v[12:13], s[4:5], 0, v[16:17]
	global_load_dwordx4 v[12:15], v[12:13], off
	s_waitcnt lgkmcnt(0)
	v_add_f32_e32 v0, v0, v5
	v_add_f32_e32 v1, v1, v10
	v_max_f32_e32 v0, v0, v1
	s_mov_b32 s4, 0xf800000
	v_mul_f32_e32 v1, 0x4f800000, v0
	v_cmp_gt_f32_e64 s[4:5], s4, v0
	s_mov_b32 s8, 1
	s_nop 0
	v_cndmask_b32_e64 v1, v0, v1, s[4:5]
	v_sqrt_f32_e32 v5, v1
	v_mov_b32_e32 v0, 0
	v_add_u32_e32 v10, -1, v5
	v_fma_f32 v19, -v10, v5, v1
	v_cmp_ge_f32_e64 s[6:7], 0, v19
	v_add_u32_e32 v19, 1, v5
	s_nop 0
	v_cndmask_b32_e64 v10, v5, v10, s[6:7]
	v_fma_f32 v5, -v19, v5, v1
	v_cmp_lt_f32_e64 s[6:7], 0, v5
	s_nop 1
	v_cndmask_b32_e64 v5, v10, v19, s[6:7]
	v_mul_f32_e32 v10, 0x37800000, v5
	v_cndmask_b32_e64 v5, v5, v10, s[4:5]
	v_cmp_class_f32_e64 s[4:5], v1, v200
	s_nop 1
	v_cndmask_b32_e64 v1, v5, v1, s[4:5]
	v_mul_f32_e32 v1, v9, v1
	v_mul_f32_e32 v1, 0x411cc471, v1
	s_movk_i32 s4, 0x88
	v_mul_f32_e32 v64, 0xbf8147ae, v1
	v_mul_lo_u32 v1, v11, s4
	v_lshl_add_u32 v209, v18, 4, v1
	v_mov_b32_e32 v65, v64
	v_mov_b32_e32 v66, v64
	v_mov_b32_e32 v67, v64
	v_mov_b32_e32 v68, v64
	v_mov_b32_e32 v69, v64
	v_mov_b32_e32 v70, v64
	v_mov_b32_e32 v71, v64
	v_mov_b32_e32 v72, v64
	v_mov_b32_e32 v73, v64
	v_mov_b32_e32 v74, v64
	v_mov_b32_e32 v75, v64
	v_mov_b32_e32 v76, v64
	v_mov_b32_e32 v77, v64
	v_mov_b32_e32 v78, v64
	v_mov_b32_e32 v79, v64
	s_lshr_b32 s4, s63, 2
	v_add_u32_e32 v1, 0x3000, v209
	s_mul_hi_u32 s5, s4, 0x48000
	s_mul_i32 s6, s4, 0x48000
	s_mul_hi_u32 s7, s4, 0x6c000
	s_mul_i32 s9, s4, 0x6c000
	s_add_u32 s4, s60, s6
	s_waitcnt vmcnt(0)
	ds_write2_b64 v1, v[12:13], v[14:15] offset1:1
	v_lshrrev_b32_e32 v1, 2, v7
	s_addc_u32 s5, s61, s5
	v_lshlrev_b32_e32 v5, 2, v7
	v_xor_b32_e32 v1, v8, v1
	v_lshl_add_u64 v[170:171], s[4:5], 0, v[16:17]
	s_add_u32 s4, s64, s9
	v_and_b32_e32 v210, 32, v5
	v_lshlrev_b32_e32 v1, 4, v1
	s_addc_u32 s5, s65, s7
	v_lshlrev_b32_e32 v168, 1, v4
	v_and_b32_e32 v211, 16, v1
	v_mul_i32_i24_e32 v206, -2, v210
	v_mul_u32_u24_e32 v212, 0xc0, v6
	v_mul_u32_u24_e32 v208, 0x88, v6
	v_mad_u32_u24 v207, v6, s58, v205
	v_lshl_add_u64 v[172:173], v[2:3], 1, s[4:5]
	v_lshl_add_u64 v[174:175], s[4:5], 0, v[168:169]
	v_mov_b32_e32 v1, v0
	v_mov_b32_e32 v2, v0
	v_mov_b32_e32 v3, v0
	v_mov_b32_e32 v4, v0
	v_mov_b32_e32 v5, v0
	v_mov_b32_e32 v6, v0
	v_mov_b32_e32 v7, v0
	v_mov_b32_e32 v8, v0
	v_mov_b32_e32 v9, v0
	v_mov_b32_e32 v10, v0
	v_mov_b32_e32 v11, v0
	v_mov_b32_e32 v12, v0
	v_mov_b32_e32 v13, v0
	v_mov_b32_e32 v14, v0
	v_mov_b32_e32 v15, v0
	v_mov_b32_e32 v32, v0
	v_mov_b32_e32 v33, v0
	v_mov_b32_e32 v34, v0
	v_mov_b32_e32 v35, v0
	v_mov_b32_e32 v36, v0
	v_mov_b32_e32 v37, v0
	v_mov_b32_e32 v38, v0
	v_mov_b32_e32 v39, v0
	v_mov_b32_e32 v40, v0
	v_mov_b32_e32 v41, v0
	v_mov_b32_e32 v42, v0
	v_mov_b32_e32 v43, v0
	v_mov_b32_e32 v44, v0
	v_mov_b32_e32 v45, v0
	v_mov_b32_e32 v46, v0
	v_mov_b32_e32 v47, v0
	v_mov_b32_e32 v48, v0
	v_mov_b32_e32 v49, v0
	v_mov_b32_e32 v50, v0
	v_mov_b32_e32 v51, v0
	v_mov_b32_e32 v52, v0
	v_mov_b32_e32 v53, v0
	v_mov_b32_e32 v54, v0
	v_mov_b32_e32 v55, v0
	v_mov_b32_e32 v56, v0
	v_mov_b32_e32 v57, v0
	v_mov_b32_e32 v58, v0
	v_mov_b32_e32 v59, v0
	v_mov_b32_e32 v60, v0
	v_mov_b32_e32 v61, v0
	v_mov_b32_e32 v62, v0
	v_mov_b32_e32 v63, v0
	v_mov_b32_e32 v16, v0
	v_mov_b32_e32 v17, v0
	v_mov_b32_e32 v18, v0
	v_mov_b32_e32 v19, v0
	v_mov_b32_e32 v20, v0
	v_mov_b32_e32 v21, v0
	v_mov_b32_e32 v22, v0
	v_mov_b32_e32 v23, v0
	v_mov_b32_e32 v24, v0
	v_mov_b32_e32 v25, v0
	v_mov_b32_e32 v26, v0
	v_mov_b32_e32 v27, v0
	v_mov_b32_e32 v28, v0
	v_mov_b32_e32 v29, v0
	v_mov_b32_e32 v30, v0
	v_mov_b32_e32 v31, v0
	v_mov_b32_e32 v166, v0
	v_mov_b32_e32 v167, v0
	s_waitcnt lgkmcnt(0)
	v_readfirstlane_b32 s101, v220
	s_barrier
	s_branch .LBB0_549

; #define GLDS(gp, lp) __builtin_amdgcn_global_load_lds((const unsigned*)(gp), (__attribute__((address_space(3))) unsigned*)(lp), 16, 0, 0)
; #define SB_ __builtin_amdgcn_sched_barrier(0)
; DI void attn_item64(const Params& p, int it, char* smem) {
;     ...
;   for (int kt = 0; kt < NKT; ++kt) {
;     const char* cur = smem + (kt & 1) * STAGE;
;     const bool more = kt + 1 < NKT;
;     if (more) {
;       const bf16_t* kn = Kb + (size_t)(kt + 1) * 64 * QKD; const bf16_t* vn = Vb + (kt + 1) * 64;
;       char* nx = smem + ((kt + 1) & 1) * STAGE;
;       GLDS(kn + kgo0, nx + klo0); if (k1v) GLDS(kn + kgo1, nx + klo1);
;       rv0 = *(const uint4*)(vn + vgo0);
;     }
;     SB_;
.LBB0_549:
	s_cmp_lt_u32 s101, 0x100
	s_cbranch_scc1 .Lattn_nolag
	s_sleep 6
